# stack7: + nt on P1 conv-input/q epilogue stores (keeps K/V tiles cache-resident for attention)
# speedup vs baseline: 1.0347x; 1.0053x over previous
; DI unsigned pack2(float a, float b) { const f32x2 v = {a, b}; const bf16x2_t r = __builtin_convertvector(v, bf16x2_t); return __builtin_bit_cast(unsigned, r); }
; DI void inproj_epilogue(const Params& p, const char* smem, const int m0, const int n0) {
;     ...
;   if (n0 < 1536) {
;     u16* dst = n0 < 1024 ? (pu + (size_t)m0 * 1024 + n0) : (qb + (size_t)m0 * 512 + (n0 - 1024));
;     const int ld = n0 < 1024 ? 1024 : 512;
; #pragma unroll 4
;     for (int i = 0; i < 16; ++i) {
;       const int c = threadIdx.x + NT * i, row = c >> 5, ch = c & 31;
;       const float4 y = *(const float4*)(ct + row * CT_PITCH + 4 * ch), bv = *(const float4*)(p.b_in + n0 + 4 * ch);
;       uint2 r; r.x = pack2(y.x + bv.x, y.y + bv.y); r.y = pack2(y.z + bv.z, y.w + bv.w);
;       *(uint2*)(dst + (size_t)row * ld + 4 * ch) = r;
;     }
;     return;
.LBB0_86:
	v_lshrrev_b32_e32 v228, 4, v0
	v_and_b32_e32 v229, 15, v0
	v_mul_lo_u32 v227, v228, s84
	v_lshlrev_b32_e32 v226, 5, v229
	v_mul_u32_u24_e32 v228, 0x210, v228
	v_lshlrev_b32_e32 v227, 1, v227
	v_add_u32_e32 v226, v228, v226
	v_lshl_add_u32 v227, v229, 4, v227
	v_lshl_add_u32 v228, v229, 3, s78
	v_lshlrev_b32_e32 v228, 2, v228
	global_load_dwordx4 v[248:251], v228, s[56:57]
	global_load_dwordx4 v[252:255], v228, s[56:57] offset:16
	s_mov_b64 s[98:99], s[82:83]
	s_lshl_b32 s100, s84, 6
	ds_read_b128 v[240:243], v226
	ds_read_b128 v[244:247], v226 offset:16
	s_waitcnt vmcnt(0)
	s_waitcnt lgkmcnt(0)
	v_pk_add_f32 v[240:241], v[240:241], v[248:249]
	v_pk_add_f32 v[242:243], v[242:243], v[250:251]
	v_pk_add_f32 v[244:245], v[244:245], v[252:253]
	v_pk_add_f32 v[246:247], v[246:247], v[254:255]
	v_cvt_pk_bf16_f32 v230, v240, v241
	v_cvt_pk_bf16_f32 v231, v242, v243
	v_cvt_pk_bf16_f32 v232, v244, v245
	v_cvt_pk_bf16_f32 v233, v246, v247
	v_add_u32_e32 v226, 0x4200, v226
	ds_read_b128 v[240:243], v226
	ds_read_b128 v[244:247], v226 offset:16
	global_store_dwordx4 v227, v[230:233], s[98:99] nt
	s_add_u32 s98, s98, s100
	s_addc_u32 s99, s99, 0
	s_waitcnt lgkmcnt(0)
	v_pk_add_f32 v[240:241], v[240:241], v[248:249]
	v_pk_add_f32 v[242:243], v[242:243], v[250:251]
	v_pk_add_f32 v[244:245], v[244:245], v[252:253]
	v_pk_add_f32 v[246:247], v[246:247], v[254:255]
	v_cvt_pk_bf16_f32 v234, v240, v241
	v_cvt_pk_bf16_f32 v235, v242, v243
	v_cvt_pk_bf16_f32 v236, v244, v245
	v_cvt_pk_bf16_f32 v237, v246, v247
	v_add_u32_e32 v226, 0x4200, v226
	ds_read_b128 v[240:243], v226
	ds_read_b128 v[244:247], v226 offset:16
	global_store_dwordx4 v227, v[234:237], s[98:99] nt
	s_add_u32 s98, s98, s100
	s_addc_u32 s99, s99, 0
	s_waitcnt lgkmcnt(0)
	v_pk_add_f32 v[240:241], v[240:241], v[248:249]
	v_pk_add_f32 v[242:243], v[242:243], v[250:251]
	v_pk_add_f32 v[244:245], v[244:245], v[252:253]
	v_pk_add_f32 v[246:247], v[246:247], v[254:255]
	v_cvt_pk_bf16_f32 v230, v240, v241
	v_cvt_pk_bf16_f32 v231, v242, v243
	v_cvt_pk_bf16_f32 v232, v244, v245
	v_cvt_pk_bf16_f32 v233, v246, v247
	v_add_u32_e32 v226, 0x4200, v226
	ds_read_b128 v[240:243], v226
	ds_read_b128 v[244:247], v226 offset:16
	global_store_dwordx4 v227, v[230:233], s[98:99] nt
	s_add_u32 s98, s98, s100
	s_addc_u32 s99, s99, 0
	s_waitcnt lgkmcnt(0)
	v_pk_add_f32 v[240:241], v[240:241], v[248:249]
	v_pk_add_f32 v[242:243], v[242:243], v[250:251]
	v_pk_add_f32 v[244:245], v[244:245], v[252:253]
	v_pk_add_f32 v[246:247], v[246:247], v[254:255]
	v_cvt_pk_bf16_f32 v234, v240, v241
	v_cvt_pk_bf16_f32 v235, v242, v243
	v_cvt_pk_bf16_f32 v236, v244, v245
	v_cvt_pk_bf16_f32 v237, v246, v247
	v_add_u32_e32 v226, 0x4200, v226
	ds_read_b128 v[240:243], v226
	ds_read_b128 v[244:247], v226 offset:16
	global_store_dwordx4 v227, v[234:237], s[98:99] nt
	s_add_u32 s98, s98, s100
	s_addc_u32 s99, s99, 0
	s_waitcnt lgkmcnt(0)
	v_pk_add_f32 v[240:241], v[240:241], v[248:249]
	v_pk_add_f32 v[242:243], v[242:243], v[250:251]
	v_pk_add_f32 v[244:245], v[244:245], v[252:253]
	v_pk_add_f32 v[246:247], v[246:247], v[254:255]
	v_cvt_pk_bf16_f32 v230, v240, v241
	v_cvt_pk_bf16_f32 v231, v242, v243
	v_cvt_pk_bf16_f32 v232, v244, v245
	v_cvt_pk_bf16_f32 v233, v246, v247
	v_add_u32_e32 v226, 0x4200, v226
	ds_read_b128 v[240:243], v226
	ds_read_b128 v[244:247], v226 offset:16
	global_store_dwordx4 v227, v[230:233], s[98:99] nt
	s_add_u32 s98, s98, s100
	s_addc_u32 s99, s99, 0
	s_waitcnt lgkmcnt(0)
	v_pk_add_f32 v[240:241], v[240:241], v[248:249]
	v_pk_add_f32 v[242:243], v[242:243], v[250:251]
	v_pk_add_f32 v[244:245], v[244:245], v[252:253]
	v_pk_add_f32 v[246:247], v[246:247], v[254:255]
	v_cvt_pk_bf16_f32 v234, v240, v241
	v_cvt_pk_bf16_f32 v235, v242, v243
	v_cvt_pk_bf16_f32 v236, v244, v245
	v_cvt_pk_bf16_f32 v237, v246, v247
	v_add_u32_e32 v226, 0x4200, v226
	ds_read_b128 v[240:243], v226
	ds_read_b128 v[244:247], v226 offset:16
	global_store_dwordx4 v227, v[234:237], s[98:99] nt
	s_add_u32 s98, s98, s100
	s_addc_u32 s99, s99, 0
	s_waitcnt lgkmcnt(0)
	v_pk_add_f32 v[240:241], v[240:241], v[248:249]
	v_pk_add_f32 v[242:243], v[242:243], v[250:251]
	v_pk_add_f32 v[244:245], v[244:245], v[252:253]
	v_pk_add_f32 v[246:247], v[246:247], v[254:255]
	v_cvt_pk_bf16_f32 v230, v240, v241
	v_cvt_pk_bf16_f32 v231, v242, v243
	v_cvt_pk_bf16_f32 v232, v244, v245
	v_cvt_pk_bf16_f32 v233, v246, v247
	v_add_u32_e32 v226, 0x4200, v226
	ds_read_b128 v[240:243], v226
	ds_read_b128 v[244:247], v226 offset:16
	global_store_dwordx4 v227, v[230:233], s[98:99] nt
	s_add_u32 s98, s98, s100
	s_addc_u32 s99, s99, 0
	s_waitcnt lgkmcnt(0)
	v_pk_add_f32 v[240:241], v[240:241], v[248:249]
	v_pk_add_f32 v[242:243], v[242:243], v[250:251]
	v_pk_add_f32 v[244:245], v[244:245], v[252:253]
	v_pk_add_f32 v[246:247], v[246:247], v[254:255]
	v_cvt_pk_bf16_f32 v234, v240, v241
	v_cvt_pk_bf16_f32 v235, v242, v243
	v_cvt_pk_bf16_f32 v236, v244, v245
	v_cvt_pk_bf16_f32 v237, v246, v247
	global_store_dwordx4 v227, v[234:237], s[98:99] nt

; DI unsigned pack2(float a, float b) { const f32x2 v = {a, b}; const bf16x2_t r = __builtin_convertvector(v, bf16x2_t); return __builtin_bit_cast(unsigned, r); }
; DI void inproj_epilogue(const Params& p, const char* smem, const int m0, const int n0) {
;     ...
;   if (n0 < 1536) {
;     u16* dst = n0 < 1024 ? (pu + (size_t)m0 * 1024 + n0) : (qb + (size_t)m0 * 512 + (n0 - 1024));
;     const int ld = n0 < 1024 ? 1024 : 512;
; #pragma unroll 4
;     for (int i = 0; i < 16; ++i) {
;       const int c = threadIdx.x + NT * i, row = c >> 5, ch = c & 31;
;       const float4 y = *(const float4*)(ct + row * CT_PITCH + 4 * ch), bv = *(const float4*)(p.b_in + n0 + 4 * ch);
;       uint2 r; r.x = pack2(y.x + bv.x, y.y + bv.y); r.y = pack2(y.z + bv.z, y.w + bv.w);
;       *(uint2*)(dst + (size_t)row * ld + 4 * ch) = r;
;     }
;     return;
.LBB0_104:
	v_lshrrev_b32_e32 v228, 4, v0
	v_and_b32_e32 v229, 15, v0
	v_mul_lo_u32 v227, v228, s86
	v_lshlrev_b32_e32 v226, 5, v229
	v_mul_u32_u24_e32 v228, 0x210, v228
	v_lshlrev_b32_e32 v227, 1, v227
	v_add_u32_e32 v226, v228, v226
	v_lshl_add_u32 v227, v229, 4, v227
	v_lshl_add_u32 v228, v229, 3, s82
	v_lshlrev_b32_e32 v228, 2, v228
	global_load_dwordx4 v[248:251], v228, s[56:57]
	global_load_dwordx4 v[252:255], v228, s[56:57] offset:16
	s_mov_b64 s[98:99], s[84:85]
	s_lshl_b32 s100, s86, 6
	ds_read_b128 v[240:243], v226
	ds_read_b128 v[244:247], v226 offset:16
	s_waitcnt vmcnt(0)
	s_waitcnt lgkmcnt(0)
	v_pk_add_f32 v[240:241], v[240:241], v[248:249]
	v_pk_add_f32 v[242:243], v[242:243], v[250:251]
	v_pk_add_f32 v[244:245], v[244:245], v[252:253]
	v_pk_add_f32 v[246:247], v[246:247], v[254:255]
	v_cvt_pk_bf16_f32 v230, v240, v241
	v_cvt_pk_bf16_f32 v231, v242, v243
	v_cvt_pk_bf16_f32 v232, v244, v245
	v_cvt_pk_bf16_f32 v233, v246, v247
	v_add_u32_e32 v226, 0x4200, v226
	ds_read_b128 v[240:243], v226
	ds_read_b128 v[244:247], v226 offset:16
	global_store_dwordx4 v227, v[230:233], s[98:99] nt
	s_add_u32 s98, s98, s100
	s_addc_u32 s99, s99, 0
	s_waitcnt lgkmcnt(0)
	v_pk_add_f32 v[240:241], v[240:241], v[248:249]
	v_pk_add_f32 v[242:243], v[242:243], v[250:251]
	v_pk_add_f32 v[244:245], v[244:245], v[252:253]
	v_pk_add_f32 v[246:247], v[246:247], v[254:255]
	v_cvt_pk_bf16_f32 v234, v240, v241
	v_cvt_pk_bf16_f32 v235, v242, v243
	v_cvt_pk_bf16_f32 v236, v244, v245
	v_cvt_pk_bf16_f32 v237, v246, v247
	v_add_u32_e32 v226, 0x4200, v226
	ds_read_b128 v[240:243], v226
	ds_read_b128 v[244:247], v226 offset:16
	global_store_dwordx4 v227, v[234:237], s[98:99] nt
	s_add_u32 s98, s98, s100
	s_addc_u32 s99, s99, 0
	s_waitcnt lgkmcnt(0)
	v_pk_add_f32 v[240:241], v[240:241], v[248:249]
	v_pk_add_f32 v[242:243], v[242:243], v[250:251]
	v_pk_add_f32 v[244:245], v[244:245], v[252:253]
	v_pk_add_f32 v[246:247], v[246:247], v[254:255]
	v_cvt_pk_bf16_f32 v230, v240, v241
	v_cvt_pk_bf16_f32 v231, v242, v243
	v_cvt_pk_bf16_f32 v232, v244, v245
	v_cvt_pk_bf16_f32 v233, v246, v247
	v_add_u32_e32 v226, 0x4200, v226
	ds_read_b128 v[240:243], v226
	ds_read_b128 v[244:247], v226 offset:16
	global_store_dwordx4 v227, v[230:233], s[98:99] nt
	s_add_u32 s98, s98, s100
	s_addc_u32 s99, s99, 0
	s_waitcnt lgkmcnt(0)
	v_pk_add_f32 v[240:241], v[240:241], v[248:249]
	v_pk_add_f32 v[242:243], v[242:243], v[250:251]
	v_pk_add_f32 v[244:245], v[244:245], v[252:253]
	v_pk_add_f32 v[246:247], v[246:247], v[254:255]
	v_cvt_pk_bf16_f32 v234, v240, v241
	v_cvt_pk_bf16_f32 v235, v242, v243
	v_cvt_pk_bf16_f32 v236, v244, v245
	v_cvt_pk_bf16_f32 v237, v246, v247
	v_add_u32_e32 v226, 0x4200, v226
	ds_read_b128 v[240:243], v226
	ds_read_b128 v[244:247], v226 offset:16
	global_store_dwordx4 v227, v[234:237], s[98:99] nt
	s_add_u32 s98, s98, s100
	s_addc_u32 s99, s99, 0
	s_waitcnt lgkmcnt(0)
	v_pk_add_f32 v[240:241], v[240:241], v[248:249]
	v_pk_add_f32 v[242:243], v[242:243], v[250:251]
	v_pk_add_f32 v[244:245], v[244:245], v[252:253]
	v_pk_add_f32 v[246:247], v[246:247], v[254:255]
	v_cvt_pk_bf16_f32 v230, v240, v241
	v_cvt_pk_bf16_f32 v231, v242, v243
	v_cvt_pk_bf16_f32 v232, v244, v245
	v_cvt_pk_bf16_f32 v233, v246, v247
	v_add_u32_e32 v226, 0x4200, v226
	ds_read_b128 v[240:243], v226
	ds_read_b128 v[244:247], v226 offset:16
	global_store_dwordx4 v227, v[230:233], s[98:99] nt
	s_add_u32 s98, s98, s100
	s_addc_u32 s99, s99, 0
	s_waitcnt lgkmcnt(0)
	v_pk_add_f32 v[240:241], v[240:241], v[248:249]
	v_pk_add_f32 v[242:243], v[242:243], v[250:251]
	v_pk_add_f32 v[244:245], v[244:245], v[252:253]
	v_pk_add_f32 v[246:247], v[246:247], v[254:255]
	v_cvt_pk_bf16_f32 v234, v240, v241
	v_cvt_pk_bf16_f32 v235, v242, v243
	v_cvt_pk_bf16_f32 v236, v244, v245
	v_cvt_pk_bf16_f32 v237, v246, v247
	v_add_u32_e32 v226, 0x4200, v226
	ds_read_b128 v[240:243], v226
	ds_read_b128 v[244:247], v226 offset:16
	global_store_dwordx4 v227, v[234:237], s[98:99] nt
	s_add_u32 s98, s98, s100
	s_addc_u32 s99, s99, 0
	s_waitcnt lgkmcnt(0)
	v_pk_add_f32 v[240:241], v[240:241], v[248:249]
	v_pk_add_f32 v[242:243], v[242:243], v[250:251]
	v_pk_add_f32 v[244:245], v[244:245], v[252:253]
	v_pk_add_f32 v[246:247], v[246:247], v[254:255]
	v_cvt_pk_bf16_f32 v230, v240, v241
	v_cvt_pk_bf16_f32 v231, v242, v243
	v_cvt_pk_bf16_f32 v232, v244, v245
	v_cvt_pk_bf16_f32 v233, v246, v247
	v_add_u32_e32 v226, 0x4200, v226
	ds_read_b128 v[240:243], v226
	ds_read_b128 v[244:247], v226 offset:16
	global_store_dwordx4 v227, v[230:233], s[98:99] nt
	s_add_u32 s98, s98, s100
	s_addc_u32 s99, s99, 0
	s_waitcnt lgkmcnt(0)
	v_pk_add_f32 v[240:241], v[240:241], v[248:249]
	v_pk_add_f32 v[242:243], v[242:243], v[250:251]
	v_pk_add_f32 v[244:245], v[244:245], v[252:253]
	v_pk_add_f32 v[246:247], v[246:247], v[254:255]
	v_cvt_pk_bf16_f32 v234, v240, v241
	v_cvt_pk_bf16_f32 v235, v242, v243
	v_cvt_pk_bf16_f32 v236, v244, v245
	v_cvt_pk_bf16_f32 v237, v246, v247
	global_store_dwordx4 v227, v[234:237], s[98:99] nt
	s_branch .LBB0_59
